# attention PV block: 8-deep LDS read ring over dead score registers; removed two compiler-derived drain waits at unit start
# speedup vs baseline: 1.0088x; 1.0012x over previous
; #define LAS __attribute__((address_space(3)))
; #define LOADK(i) do { _Pragma("unroll") for (int j = 0; j < 4; ++j) st[j] = *(const u32x4*)(kbase + ((i) * 64 + j * 16) * 1024 + koff); } while (0)
; #define LOADV(i) do { _Pragma("unroll") for (int j = 0; j < 4; ++j) st[j] = *(const u32x4*)(vbase + (j * 64 * 256 + (i) * 64) + voff); } while (0)
; #define STOREK() do { _Pragma("unroll") for (int j = 0; j < 4; ++j) *(LAS u32x4*)(kst + j * 16 * 528) = st[j]; } while (0)
; __device__ __forceinline__ void ph_attn(const Params& p, LAS unsigned char* lds) {
;     ...
;         const bf16_t* kbase = kb + (size_t)kvb * 256 * 1024 + h * 256; const bf16_t* vbase = vt + ((size_t)kvb * 1024 + h * 256) * 256;
;     ...
;         f32x4 sc[16];
;         LOADK(0);
; #pragma unroll
;         for (int i = 0; i < 4; ++i) {
;             __syncthreads(); STOREK(); __syncthreads();
;             if (i < 3) LOADK(i + 1); else LOADV(0);
;             if (active) {
; #pragma unroll
;                 for (int sub = 0; sub < 4; ++sub) {
;                     f32x4 a = {0.f, 0.f, 0.f, 0.f};
; #pragma unroll
;                     for (int ks = 0; ks < 8; ++ks) {
;                         const bf16x8 kf = *(const LAS bf16x8*)(krd + sub * 16 * 528 + ks * 64);
;                         a = __builtin_amdgcn_mfma_f32_16x16x32_bf16(kf, qf[ks], a, 0, 0, 0);
;                     }
;                     sc[i * 4 + sub] = a;
;                 }
;             }
;         }
.LBB0_1092:
	s_ashr_i32 s5, s4, 31
	s_lshl_b64 s[16:17], s[4:5], 19
	s_add_u32 s18, s3, s16
	s_addc_u32 s19, s14, s17
	s_lshl_b64 s[4:5], s[10:11], 1
	s_add_u32 s4, s18, s4
	s_addc_u32 s5, s19, s5
	v_lshl_add_u64 v[2:3], v[182:183], 1, s[4:5]
	s_nop 0
	v_add_co_u32_e32 v108, vcc, s22, v2
	s_nop 1
	v_addc_co_u32_e32 v109, vcc, 0, v3, vcc
	global_load_dwordx4 v[100:103], v[2:3], off
	global_load_dwordx4 v[104:107], v[108:109], off
	v_add_co_u32_e32 v108, vcc, s23, v2
	s_nop 1
	v_addc_co_u32_e32 v109, vcc, 0, v3, vcc
	s_nop 0
	v_add_co_u32_e32 v112, vcc, s24, v2
	s_nop 1
	v_addc_co_u32_e32 v113, vcc, 0, v3, vcc
	global_load_dwordx4 v[108:111], v[108:109], off
	s_nop 0
	global_load_dwordx4 v[112:115], v[112:113], off
	v_add_co_u32_e32 v116, vcc, s25, v2
	s_nop 1
	v_addc_co_u32_e32 v117, vcc, 0, v3, vcc
	v_add_co_u32_e32 v118, vcc, 0x28000, v2
	s_barrier
	s_nop 0
	v_addc_co_u32_e32 v119, vcc, 0, v3, vcc
	v_add_co_u32_e32 v120, vcc, 0x30000, v2
	s_nop 1
	v_addc_co_u32_e32 v121, vcc, 0, v3, vcc
	v_add_co_u32_e32 v122, vcc, 0x38000, v2
	s_waitcnt vmcnt(3)
	ds_write_b128 v202, v[100:103]
	s_waitcnt vmcnt(2)
	ds_write_b128 v202, v[104:107] offset:8448
	s_waitcnt vmcnt(1)
	ds_write_b128 v202, v[108:111] offset:16896
	s_waitcnt vmcnt(0)
	ds_write_b128 v202, v[112:115] offset:25344
	v_addc_co_u32_e32 v123, vcc, 0, v3, vcc
	s_waitcnt lgkmcnt(0)
	s_barrier
	global_load_dwordx4 v[100:103], v[116:117], off
	global_load_dwordx4 v[104:107], v[118:119], off
	global_load_dwordx4 v[108:111], v[120:121], off
	global_load_dwordx4 v[112:115], v[122:123], off
	s_and_b64 vcc, exec, s[12:13]
	s_cbranch_vccz .LBB0_1094
	ds_read_b128 v[48:51], v193
	ds_read_b128 v[64:67], v193 offset:64
	ds_read_b128 v[80:83], v193 offset:8448
	ds_read_b128 v[96:99], v193 offset:8512
	ds_read_b128 v[116:119], v193 offset:128
	ds_read_b128 v[120:123], v193 offset:25472
	s_waitcnt lgkmcnt(5)
	v_mfma_f32_16x16x32_bf16 v[48:51], v[48:51], v[32:35], 0
	s_waitcnt lgkmcnt(4)
	v_mfma_f32_16x16x32_bf16 v[48:51], v[64:67], v[28:31], v[48:51]
	ds_read_b128 v[64:67], v193 offset:192
	s_waitcnt lgkmcnt(2)
	v_mfma_f32_16x16x32_bf16 v[48:51], v[116:119], v[24:27], v[48:51]
	ds_read_b128 v[116:119], v193 offset:256
	v_mfma_f32_16x16x32_bf16 v[80:83], v[80:83], v[32:35], 0
	s_waitcnt lgkmcnt(1)
	v_mfma_f32_16x16x32_bf16 v[48:51], v[64:67], v[20:23], v[48:51]
	ds_read_b128 v[64:67], v193 offset:320
	s_waitcnt lgkmcnt(1)
	v_mfma_f32_16x16x32_bf16 v[48:51], v[116:119], v[16:19], v[48:51]
	ds_read_b128 v[116:119], v193 offset:384
	s_waitcnt lgkmcnt(1)
	v_mfma_f32_16x16x32_bf16 v[48:51], v[64:67], v[12:15], v[48:51]
	ds_read_b128 v[64:67], v193 offset:448
	s_waitcnt lgkmcnt(1)
	v_mfma_f32_16x16x32_bf16 v[48:51], v[116:119], v[8:11], v[48:51]
	ds_read_b128 v[116:119], v193 offset:17024
	s_waitcnt lgkmcnt(1)
	v_mfma_f32_16x16x32_bf16 v[48:51], v[64:67], v[4:7], v[48:51]
	ds_read_b128 v[64:67], v193 offset:8576
	v_mfma_f32_16x16x32_bf16 v[80:83], v[96:99], v[28:31], v[80:83]
	ds_read_b128 v[96:99], v193 offset:8640
	s_waitcnt lgkmcnt(1)
	v_mfma_f32_16x16x32_bf16 v[64:67], v[64:67], v[24:27], v[80:83]
	s_nop 4
	ds_read_b128 v[80:83], v193 offset:8704
	s_waitcnt lgkmcnt(1)
	v_mfma_f32_16x16x32_bf16 v[64:67], v[96:99], v[20:23], v[64:67]
	ds_read_b128 v[96:99], v193 offset:8768
	s_waitcnt lgkmcnt(1)
	v_mfma_f32_16x16x32_bf16 v[64:67], v[80:83], v[16:19], v[64:67]
	ds_read_b128 v[80:83], v193 offset:8832
	s_waitcnt lgkmcnt(1)
	v_mfma_f32_16x16x32_bf16 v[64:67], v[96:99], v[12:15], v[64:67]
	ds_read_b128 v[96:99], v193 offset:8896
	s_waitcnt lgkmcnt(1)
	v_mfma_f32_16x16x32_bf16 v[64:67], v[80:83], v[8:11], v[64:67]
	ds_read_b128 v[80:83], v193 offset:16896
	s_waitcnt lgkmcnt(1)
	v_mfma_f32_16x16x32_bf16 v[64:67], v[96:99], v[4:7], v[64:67]
	ds_read_b128 v[96:99], v193 offset:16960
	s_waitcnt lgkmcnt(1)
	v_mfma_f32_16x16x32_bf16 v[80:83], v[80:83], v[32:35], 0
	s_waitcnt lgkmcnt(0)
	v_mfma_f32_16x16x32_bf16 v[80:83], v[96:99], v[28:31], v[80:83]
	ds_read_b128 v[96:99], v193 offset:17088
	v_mfma_f32_16x16x32_bf16 v[80:83], v[116:119], v[24:27], v[80:83]
	ds_read_b128 v[116:119], v193 offset:17152
	s_waitcnt lgkmcnt(1)
	v_mfma_f32_16x16x32_bf16 v[80:83], v[96:99], v[20:23], v[80:83]
	ds_read_b128 v[96:99], v193 offset:17216
	s_waitcnt lgkmcnt(1)
	v_mfma_f32_16x16x32_bf16 v[80:83], v[116:119], v[16:19], v[80:83]
	ds_read_b128 v[116:119], v193 offset:17280
	s_waitcnt lgkmcnt(1)
	v_mfma_f32_16x16x32_bf16 v[80:83], v[96:99], v[12:15], v[80:83]
	ds_read_b128 v[96:99], v193 offset:17344
	s_waitcnt lgkmcnt(1)
	v_mfma_f32_16x16x32_bf16 v[80:83], v[116:119], v[8:11], v[80:83]
	ds_read_b128 v[116:119], v193 offset:25344
	s_waitcnt lgkmcnt(1)
	v_mfma_f32_16x16x32_bf16 v[80:83], v[96:99], v[4:7], v[80:83]
	ds_read_b128 v[96:99], v193 offset:25408
	s_waitcnt lgkmcnt(1)
	v_mfma_f32_16x16x32_bf16 v[116:119], v[116:119], v[32:35], 0
	s_waitcnt lgkmcnt(0)
	v_mfma_f32_16x16x32_bf16 v[96:99], v[96:99], v[28:31], v[116:119]
	s_nop 5
	ds_read_b128 v[116:119], v193 offset:25536
	v_mfma_f32_16x16x32_bf16 v[96:99], v[120:123], v[24:27], v[96:99]
	ds_read_b128 v[120:123], v193 offset:25600
	s_waitcnt lgkmcnt(1)
	v_mfma_f32_16x16x32_bf16 v[96:99], v[116:119], v[20:23], v[96:99]
	ds_read_b128 v[116:119], v193 offset:25664
	s_waitcnt lgkmcnt(1)
	v_mfma_f32_16x16x32_bf16 v[96:99], v[120:123], v[16:19], v[96:99]
	ds_read_b128 v[120:123], v193 offset:25728
	s_waitcnt lgkmcnt(1)
	v_mfma_f32_16x16x32_bf16 v[96:99], v[116:119], v[12:15], v[96:99]
	ds_read_b128 v[116:119], v193 offset:25792
	s_waitcnt lgkmcnt(1)
	v_mfma_f32_16x16x32_bf16 v[96:99], v[120:123], v[8:11], v[96:99]
	s_waitcnt lgkmcnt(0)
	v_mfma_f32_16x16x32_bf16 v[96:99], v[116:119], v[4:7], v[96:99]

; #define LAS __attribute__((address_space(3)))
; #define LOADV(i) do { _Pragma("unroll") for (int j = 0; j < 4; ++j) st[j] = *(const u32x4*)(vbase + (j * 64 * 256 + (i) * 64) + voff); } while (0)
; #define STOREV() do { _Pragma("unroll") for (int j = 0; j < 4; ++j) *(LAS u32x4*)(vst + j * 64 * 144) = st[j]; } while (0)
; __device__ __forceinline__ void ph_attn(const Params& p, LAS unsigned char* lds) {
;     ...
; #pragma unroll 1
;         for (int i = 0; i < 4; ++i) {
;             __syncthreads(); STOREV(); __syncthreads();
;             if (i < 3) LOADV(i + 1);
;             if (active) {
; #pragma unroll
;                 for (int ks = 0; ks < 2; ++ks) {
;                     const bf16x8 pf = *(const LAS bf16x8*)(pw + fq * 8 + i * 128 + ks * 64);
; #pragma unroll
;                     for (int dt = 0; dt < 16; ++dt) {
;                         const bf16x8 vf = *(const LAS bf16x8*)(vrd + dt * 16 * 144 + ks * 64);
;                         oa[dt] = __builtin_amdgcn_mfma_f32_16x16x32_bf16(vf, pf, oa[dt], 0, 0, 0);
;                     }
;                 }
;             }
;         }
.LBB0_1106:
	s_and_b64 vcc, exec, s[4:5]
	s_cbranch_vccnz .LBB0_1103
	ds_read_b128 v[208:211], v187
	ds_read_b128 v[212:215], v187 offset:64
	ds_read_b128 v[36:39], v201
	ds_read_b128 v[40:43], v201 offset:2304
	ds_read_b128 v[44:47], v201 offset:4608
	ds_read_b128 v[48:51], v201 offset:6912
	ds_read_b128 v[52:55], v201 offset:9216
	ds_read_b128 v[56:59], v201 offset:11520
	ds_read_b128 v[60:63], v201 offset:13824
	ds_read_b128 v[64:67], v201 offset:16128
	s_waitcnt lgkmcnt(7)
	v_mfma_f32_16x16x32_bf16 v[176:179], v[36:39], v[208:211], v[176:179]
	ds_read_b128 v[68:71], v201 offset:18432
	s_waitcnt lgkmcnt(7)
	v_mfma_f32_16x16x32_bf16 v[172:175], v[40:43], v[208:211], v[172:175]
	ds_read_b128 v[72:75], v201 offset:20736
	s_waitcnt lgkmcnt(7)
	v_mfma_f32_16x16x32_bf16 v[168:171], v[44:47], v[208:211], v[168:171]
	ds_read_b128 v[76:79], v201 offset:23040
	s_waitcnt lgkmcnt(7)
	v_mfma_f32_16x16x32_bf16 v[164:167], v[48:51], v[208:211], v[164:167]
	ds_read_b128 v[80:83], v201 offset:25344
	s_waitcnt lgkmcnt(7)
	v_mfma_f32_16x16x32_bf16 v[160:163], v[52:55], v[208:211], v[160:163]
	ds_read_b128 v[84:87], v201 offset:27648
	s_waitcnt lgkmcnt(7)
	v_mfma_f32_16x16x32_bf16 v[156:159], v[56:59], v[208:211], v[156:159]
	ds_read_b128 v[88:91], v201 offset:29952
	s_waitcnt lgkmcnt(7)
	v_mfma_f32_16x16x32_bf16 v[152:155], v[60:63], v[208:211], v[152:155]
	ds_read_b128 v[92:95], v201 offset:32256
	s_waitcnt lgkmcnt(7)
	v_mfma_f32_16x16x32_bf16 v[148:151], v[64:67], v[208:211], v[148:151]
	ds_read_b128 v[96:99], v201 offset:34560
	s_waitcnt lgkmcnt(7)
	v_mfma_f32_16x16x32_bf16 v[144:147], v[68:71], v[208:211], v[144:147]
	ds_read_b128 v[36:39], v201 offset:64
	s_waitcnt lgkmcnt(7)
	v_mfma_f32_16x16x32_bf16 v[140:143], v[72:75], v[208:211], v[140:143]
	ds_read_b128 v[40:43], v201 offset:2368
	s_waitcnt lgkmcnt(7)
	v_mfma_f32_16x16x32_bf16 v[136:139], v[76:79], v[208:211], v[136:139]
	ds_read_b128 v[44:47], v201 offset:4672
	s_waitcnt lgkmcnt(7)
	v_mfma_f32_16x16x32_bf16 v[132:135], v[80:83], v[208:211], v[132:135]
	ds_read_b128 v[48:51], v201 offset:6976
	s_waitcnt lgkmcnt(7)
	v_mfma_f32_16x16x32_bf16 v[128:131], v[84:87], v[208:211], v[128:131]
	ds_read_b128 v[52:55], v201 offset:9280
	s_waitcnt lgkmcnt(7)
	v_mfma_f32_16x16x32_bf16 v[124:127], v[88:91], v[208:211], v[124:127]
	ds_read_b128 v[56:59], v201 offset:11584
	s_waitcnt lgkmcnt(7)
	v_mfma_f32_16x16x32_bf16 v[120:123], v[92:95], v[208:211], v[120:123]
	ds_read_b128 v[60:63], v201 offset:13888
	s_waitcnt lgkmcnt(7)
	v_mfma_f32_16x16x32_bf16 v[116:119], v[96:99], v[208:211], v[116:119]
	ds_read_b128 v[64:67], v201 offset:16192
	s_waitcnt lgkmcnt(7)
	v_mfma_f32_16x16x32_bf16 v[176:179], v[36:39], v[212:215], v[176:179]
	ds_read_b128 v[68:71], v201 offset:18496
	s_waitcnt lgkmcnt(7)
	v_mfma_f32_16x16x32_bf16 v[172:175], v[40:43], v[212:215], v[172:175]
	ds_read_b128 v[72:75], v201 offset:20800
	s_waitcnt lgkmcnt(7)
	v_mfma_f32_16x16x32_bf16 v[168:171], v[44:47], v[212:215], v[168:171]
	ds_read_b128 v[76:79], v201 offset:23104
	s_waitcnt lgkmcnt(7)
	v_mfma_f32_16x16x32_bf16 v[164:167], v[48:51], v[212:215], v[164:167]
	ds_read_b128 v[80:83], v201 offset:25408
	s_waitcnt lgkmcnt(7)
	v_mfma_f32_16x16x32_bf16 v[160:163], v[52:55], v[212:215], v[160:163]
	ds_read_b128 v[84:87], v201 offset:27712
	s_waitcnt lgkmcnt(7)
	v_mfma_f32_16x16x32_bf16 v[156:159], v[56:59], v[212:215], v[156:159]
	ds_read_b128 v[88:91], v201 offset:30016
	s_waitcnt lgkmcnt(7)
	v_mfma_f32_16x16x32_bf16 v[152:155], v[60:63], v[212:215], v[152:155]
	ds_read_b128 v[92:95], v201 offset:32320
	s_waitcnt lgkmcnt(7)
	v_mfma_f32_16x16x32_bf16 v[148:151], v[64:67], v[212:215], v[148:151]
	ds_read_b128 v[96:99], v201 offset:34624
	s_waitcnt lgkmcnt(7)
	v_mfma_f32_16x16x32_bf16 v[144:147], v[68:71], v[212:215], v[144:147]
	s_waitcnt lgkmcnt(6)
	v_mfma_f32_16x16x32_bf16 v[140:143], v[72:75], v[212:215], v[140:143]
	s_waitcnt lgkmcnt(5)
	v_mfma_f32_16x16x32_bf16 v[136:139], v[76:79], v[212:215], v[136:139]
	s_waitcnt lgkmcnt(4)
	v_mfma_f32_16x16x32_bf16 v[132:135], v[80:83], v[212:215], v[132:135]
	s_waitcnt lgkmcnt(3)
	v_mfma_f32_16x16x32_bf16 v[128:131], v[84:87], v[212:215], v[128:131]
	s_waitcnt lgkmcnt(2)
	v_mfma_f32_16x16x32_bf16 v[124:127], v[88:91], v[212:215], v[124:127]
	s_waitcnt lgkmcnt(1)
	v_mfma_f32_16x16x32_bf16 v[120:123], v[92:95], v[212:215], v[120:123]
	s_waitcnt lgkmcnt(0)
	v_mfma_f32_16x16x32_bf16 v[116:119], v[96:99], v[212:215], v[116:119]
	s_branch .LBB0_1103
